# GEMM1 units of the padded column (un=13) run a K-loop copy without the unused gate-half MFMAs, LDS reads and gate-half operand loads
# speedup vs baseline: 1.0037x; 1.0037x over previous
.LBB0_619:
	s_ashr_i32 s39, s38, 31
	s_lshl_b64 s[2:3], s[38:39], 19
	s_add_u32 s40, s58, s2
	s_addc_u32 s41, s59, s3
	s_and_b64 s[2:3], s[36:37], exec
	s_cselect_b32 s11, s41, s31
	s_cselect_b32 s18, s40, s30
	s_ashr_i32 s13, s12, 31
	s_lshl_b64 s[2:3], s[12:13], 19
	s_add_u32 s42, s6, s2
	s_addc_u32 s43, s7, s3
	s_and_b64 s[2:3], s[36:37], exec
	s_cselect_b32 s13, s43, s17
	s_cselect_b32 s19, s42, s16
	s_add_u32 s30, s30, 0x40080
	s_addc_u32 s31, s31, 0
	s_add_u32 s28, s16, 0x100
	s_addc_u32 s29, s17, 0
	s_mov_b32 s39, -2
	s_cmp_eq_u32 s10, 13
	s_cbranch_scc1 .LHM_kB
	s_add_u32 s2, s30, 0xfffc0080
	s_addc_u32 s3, s31, -1
	s_add_i32 s94, 32, 0x10000
	v_add_u32_e32 v131, s94, v145
	ds_read_b128 v[170:173], v131
	ds_read_b128 v[174:177], v131 offset:1024
	ds_read_b128 v[182:185], v131 offset:2048
	ds_read_b128 v[186:189], v131 offset:3072
	s_cmp_eq_u32 s39, 12
	s_cselect_b32 s3, s11, s3
	s_cselect_b32 s2, s18, s2
	s_cselect_b32 s17, s13, s29
	s_cselect_b32 s16, s19, s28
	s_add_i32 m0, s35, 0xc000
	ds_read_b128 v[190:193], v151
	ds_read_b128 v[194:197], v151 offset:1024
	ds_read_b128 v[198:201], v151 offset:2048
	ds_read_b128 v[202:205], v151 offset:3072
	ds_read_b128 v[206:209], v151 offset:4096
	ds_read_b128 v[210:213], v151 offset:5120
	ds_read_b128 v[214:217], v151 offset:6144
	ds_read_b128 v[218:221], v151 offset:7168
	global_load_lds_dwordx4 v140, s[30:31]
	s_add_i32 m0, s35, 0xe000
	s_nop 0
	global_load_lds_dwordx4 v142, s[30:31]
	s_waitcnt lgkmcnt(8)
	s_barrier
	s_waitcnt lgkmcnt(0)
	s_waitcnt lgkmcnt(0)
	v_mfma_f32_16x16x32_bf16 v[126:129], v[170:173], v[190:193], 0
	v_mfma_f32_16x16x32_bf16 v[122:125], v[182:185], v[190:193], 0
	v_mfma_f32_16x16x32_bf16 v[110:113], v[170:173], v[198:201], 0
	v_mfma_f32_16x16x32_bf16 v[106:109], v[182:185], v[198:201], 0
	v_mfma_f32_16x16x32_bf16 v[94:97], v[170:173], v[206:209], 0
	v_mfma_f32_16x16x32_bf16 v[90:93], v[182:185], v[206:209], 0
	v_mfma_f32_16x16x32_bf16 v[78:81], v[170:173], v[214:217], 0
	v_mfma_f32_16x16x32_bf16 v[74:77], v[182:185], v[214:217], 0
	v_mfma_f32_16x16x32_bf16 v[126:129], v[174:177], v[194:197], v[126:129]
	v_mfma_f32_16x16x32_bf16 v[122:125], v[186:189], v[194:197], v[122:125]
	v_mfma_f32_16x16x32_bf16 v[110:113], v[174:177], v[202:205], v[110:113]
	v_mfma_f32_16x16x32_bf16 v[106:109], v[186:189], v[202:205], v[106:109]
	v_mfma_f32_16x16x32_bf16 v[94:97], v[174:177], v[210:213], v[94:97]
	v_mfma_f32_16x16x32_bf16 v[90:93], v[186:189], v[210:213], v[90:93]
	v_mfma_f32_16x16x32_bf16 v[78:81], v[174:177], v[218:221], v[78:81]
	v_mfma_f32_16x16x32_bf16 v[74:77], v[186:189], v[218:221], v[74:77]
	s_barrier
	s_add_i32 vcc_lo, 32, 0x14000
	s_add_i32 s94, s94, s5
	s_mov_b32 m0, s94
	ds_read_b128 v[222:225], v131 offset:16384
	ds_read_b128 v[226:229], v131 offset:17408
	ds_read_b128 v[230:233], v131 offset:18432
	ds_read_b128 v[234:237], v131 offset:19456
	global_load_lds_dwordx4 v154, s[16:17]
	s_add_i32 m0, s94, 0x2000
	s_nop 0
	global_load_lds_dwordx4 v138, s[16:17]
	s_barrier
	s_waitcnt lgkmcnt(0)
	s_waitcnt lgkmcnt(0)
	v_mfma_f32_16x16x32_bf16 v[118:121], v[222:225], v[190:193], 0
	v_mfma_f32_16x16x32_bf16 v[114:117], v[230:233], v[190:193], 0
	v_mfma_f32_16x16x32_bf16 v[102:105], v[222:225], v[198:201], 0
	v_mfma_f32_16x16x32_bf16 v[98:101], v[230:233], v[198:201], 0
	v_mfma_f32_16x16x32_bf16 v[86:89], v[222:225], v[206:209], 0
	v_mfma_f32_16x16x32_bf16 v[82:85], v[230:233], v[206:209], 0
	v_mfma_f32_16x16x32_bf16 v[70:73], v[222:225], v[214:217], 0
	v_mfma_f32_16x16x32_bf16 v[66:69], v[230:233], v[214:217], 0
	v_mfma_f32_16x16x32_bf16 v[118:121], v[226:229], v[194:197], v[118:121]
	v_mfma_f32_16x16x32_bf16 v[114:117], v[234:237], v[194:197], v[114:117]
	v_mfma_f32_16x16x32_bf16 v[102:105], v[226:229], v[202:205], v[102:105]
	v_mfma_f32_16x16x32_bf16 v[98:101], v[234:237], v[202:205], v[98:101]
	v_mfma_f32_16x16x32_bf16 v[86:89], v[226:229], v[210:213], v[86:89]
	v_mfma_f32_16x16x32_bf16 v[82:85], v[234:237], v[210:213], v[82:85]
	v_mfma_f32_16x16x32_bf16 v[70:73], v[226:229], v[218:221], v[70:73]
	v_mfma_f32_16x16x32_bf16 v[66:69], v[234:237], v[218:221], v[66:69]
	s_mov_b32 m0, s35
	s_mov_b64 s[98:99], s[2:3]
	s_barrier
	ds_read_b128 v[190:193], v151 offset:16384
	ds_read_b128 v[194:197], v151 offset:17408
	ds_read_b128 v[198:201], v151 offset:18432
	ds_read_b128 v[202:205], v151 offset:19456
	ds_read_b128 v[206:209], v151 offset:20480
	ds_read_b128 v[210:213], v151 offset:21504
	ds_read_b128 v[214:217], v151 offset:22528
	ds_read_b128 v[218:221], v151 offset:23552
	global_load_lds_dwordx4 v134, s[2:3]
	s_mov_b32 m0, s14
	s_nop 0
	global_load_lds_dwordx4 v136, s[2:3]
	s_barrier
	s_waitcnt lgkmcnt(0)
	s_waitcnt lgkmcnt(0)
	v_mfma_f32_16x16x32_bf16 v[62:65], v[170:173], v[190:193], 0
	v_mfma_f32_16x16x32_bf16 v[58:61], v[182:185], v[190:193], 0
	v_mfma_f32_16x16x32_bf16 v[46:49], v[170:173], v[198:201], 0
	v_mfma_f32_16x16x32_bf16 v[42:45], v[182:185], v[198:201], 0
	v_mfma_f32_16x16x32_bf16 v[30:33], v[170:173], v[206:209], 0
	v_mfma_f32_16x16x32_bf16 v[26:29], v[182:185], v[206:209], 0
	v_mfma_f32_16x16x32_bf16 v[14:17], v[170:173], v[214:217], 0
	v_mfma_f32_16x16x32_bf16 v[10:13], v[182:185], v[214:217], 0
	v_mfma_f32_16x16x32_bf16 v[62:65], v[174:177], v[194:197], v[62:65]
	v_mfma_f32_16x16x32_bf16 v[58:61], v[186:189], v[194:197], v[58:61]
	v_mfma_f32_16x16x32_bf16 v[46:49], v[174:177], v[202:205], v[46:49]
	v_mfma_f32_16x16x32_bf16 v[42:45], v[186:189], v[202:205], v[42:45]
	v_mfma_f32_16x16x32_bf16 v[30:33], v[174:177], v[210:213], v[30:33]
	v_mfma_f32_16x16x32_bf16 v[26:29], v[186:189], v[210:213], v[26:29]
	v_mfma_f32_16x16x32_bf16 v[14:17], v[174:177], v[218:221], v[14:17]
	v_mfma_f32_16x16x32_bf16 v[10:13], v[186:189], v[218:221], v[10:13]
	s_barrier
	s_add_u32 s94, s16, 0x40000
	s_addc_u32 s95, s17, 0
	s_add_i32 vcc_lo, vcc_lo, s5
	s_mov_b32 m0, vcc_lo
	s_nop 0
	global_load_lds_dwordx4 v154, s[94:95]
	s_add_i32 m0, vcc_lo, 0x2000
	s_nop 0
	global_load_lds_dwordx4 v138, s[94:95]
	s_waitcnt vmcnt(6)
	s_barrier
	v_mfma_f32_16x16x32_bf16 v[54:57], v[222:225], v[190:193], 0
	v_mfma_f32_16x16x32_bf16 v[50:53], v[230:233], v[190:193], 0
	v_mfma_f32_16x16x32_bf16 v[38:41], v[222:225], v[198:201], 0
	v_mfma_f32_16x16x32_bf16 v[34:37], v[230:233], v[198:201], 0
	v_mfma_f32_16x16x32_bf16 v[22:25], v[222:225], v[206:209], 0
	v_mfma_f32_16x16x32_bf16 v[18:21], v[230:233], v[206:209], 0
	v_mfma_f32_16x16x32_bf16 v[6:9], v[222:225], v[214:217], 0
	v_mfma_f32_16x16x32_bf16 v[2:5], v[230:233], v[214:217], 0
	v_mfma_f32_16x16x32_bf16 v[54:57], v[226:229], v[194:197], v[54:57]
	v_mfma_f32_16x16x32_bf16 v[50:53], v[234:237], v[194:197], v[50:53]
	v_mfma_f32_16x16x32_bf16 v[38:41], v[226:229], v[202:205], v[38:41]
	v_mfma_f32_16x16x32_bf16 v[34:37], v[234:237], v[202:205], v[34:37]
	v_mfma_f32_16x16x32_bf16 v[22:25], v[226:229], v[210:213], v[22:25]
	v_mfma_f32_16x16x32_bf16 v[18:21], v[234:237], v[210:213], v[18:21]
	v_mfma_f32_16x16x32_bf16 v[6:9], v[226:229], v[218:221], v[6:9]
	v_mfma_f32_16x16x32_bf16 v[2:5], v[234:237], v[218:221], v[2:5]
	s_add_i32 s94, 32, 0x18000
	s_barrier
	ds_read_b128 v[170:173], v131 offset:32768
	ds_read_b128 v[174:177], v131 offset:33792
	ds_read_b128 v[182:185], v131 offset:34816
	ds_read_b128 v[186:189], v131 offset:35840
	s_add_u32 s2, s2, 0x40000
	s_addc_u32 s3, s3, 0
	s_mov_b32 m0, s4
	ds_read_b128 v[190:193], v151 offset:32768
	ds_read_b128 v[194:197], v151 offset:33792
	ds_read_b128 v[198:201], v151 offset:34816
	ds_read_b128 v[202:205], v151 offset:35840
	ds_read_b128 v[206:209], v151 offset:36864
	ds_read_b128 v[210:213], v151 offset:37888
	ds_read_b128 v[214:217], v151 offset:38912
	ds_read_b128 v[218:221], v151 offset:39936
	global_load_lds_dwordx4 v134, s[2:3]
	s_mov_b32 m0, s20
	s_nop 0
	global_load_lds_dwordx4 v136, s[2:3]
	s_waitcnt lgkmcnt(8)
	s_barrier
	s_waitcnt lgkmcnt(0)
	s_waitcnt lgkmcnt(0)
	v_mfma_f32_16x16x32_bf16 v[126:129], v[170:173], v[190:193], v[126:129]
	v_mfma_f32_16x16x32_bf16 v[122:125], v[182:185], v[190:193], v[122:125]
	v_mfma_f32_16x16x32_bf16 v[110:113], v[170:173], v[198:201], v[110:113]
	v_mfma_f32_16x16x32_bf16 v[106:109], v[182:185], v[198:201], v[106:109]
	v_mfma_f32_16x16x32_bf16 v[94:97], v[170:173], v[206:209], v[94:97]
	v_mfma_f32_16x16x32_bf16 v[90:93], v[182:185], v[206:209], v[90:93]
	v_mfma_f32_16x16x32_bf16 v[78:81], v[170:173], v[214:217], v[78:81]
	v_mfma_f32_16x16x32_bf16 v[74:77], v[182:185], v[214:217], v[74:77]
	v_mfma_f32_16x16x32_bf16 v[126:129], v[174:177], v[194:197], v[126:129]
	v_mfma_f32_16x16x32_bf16 v[122:125], v[186:189], v[194:197], v[122:125]
	v_mfma_f32_16x16x32_bf16 v[110:113], v[174:177], v[202:205], v[110:113]
	v_mfma_f32_16x16x32_bf16 v[106:109], v[186:189], v[202:205], v[106:109]
	v_mfma_f32_16x16x32_bf16 v[94:97], v[174:177], v[210:213], v[94:97]
	v_mfma_f32_16x16x32_bf16 v[90:93], v[186:189], v[210:213], v[90:93]
	v_mfma_f32_16x16x32_bf16 v[78:81], v[174:177], v[218:221], v[78:81]
	v_mfma_f32_16x16x32_bf16 v[74:77], v[186:189], v[218:221], v[74:77]
	s_barrier
	s_add_i32 s95, 32, 0x1c000
	s_add_i32 s2, s94, s5
	s_mov_b32 m0, s2
	ds_read_b128 v[222:225], v131 offset:49152
	ds_read_b128 v[226:229], v131 offset:50176
	ds_read_b128 v[230:233], v131 offset:51200
	ds_read_b128 v[234:237], v131 offset:52224
	s_add_u32 s100, s16, 128
	s_addc_u32 s101, s17, 0
	global_load_lds_dwordx4 v154, s[100:101]
	s_add_i32 m0, s2, 0x2000
	s_nop 0
	global_load_lds_dwordx4 v138, s[100:101]
	s_barrier
	s_waitcnt lgkmcnt(0)
	s_waitcnt lgkmcnt(0)
	v_mfma_f32_16x16x32_bf16 v[118:121], v[222:225], v[190:193], v[118:121]
	v_mfma_f32_16x16x32_bf16 v[114:117], v[230:233], v[190:193], v[114:117]
	v_mfma_f32_16x16x32_bf16 v[102:105], v[222:225], v[198:201], v[102:105]
	v_mfma_f32_16x16x32_bf16 v[98:101], v[230:233], v[198:201], v[98:101]
	v_mfma_f32_16x16x32_bf16 v[86:89], v[222:225], v[206:209], v[86:89]
	v_mfma_f32_16x16x32_bf16 v[82:85], v[230:233], v[206:209], v[82:85]
	v_mfma_f32_16x16x32_bf16 v[70:73], v[222:225], v[214:217], v[70:73]
	v_mfma_f32_16x16x32_bf16 v[66:69], v[230:233], v[214:217], v[66:69]
	v_mfma_f32_16x16x32_bf16 v[118:121], v[226:229], v[194:197], v[118:121]
	v_mfma_f32_16x16x32_bf16 v[114:117], v[234:237], v[194:197], v[114:117]
	v_mfma_f32_16x16x32_bf16 v[102:105], v[226:229], v[202:205], v[102:105]
	v_mfma_f32_16x16x32_bf16 v[98:101], v[234:237], v[202:205], v[98:101]
	v_mfma_f32_16x16x32_bf16 v[86:89], v[226:229], v[210:213], v[86:89]
	v_mfma_f32_16x16x32_bf16 v[82:85], v[234:237], v[210:213], v[82:85]
	v_mfma_f32_16x16x32_bf16 v[70:73], v[226:229], v[218:221], v[70:73]
	v_mfma_f32_16x16x32_bf16 v[66:69], v[234:237], v[218:221], v[66:69]
	s_mov_b32 m0, s21
	s_barrier
	ds_read_b128 v[190:193], v151 offset:49152
	ds_read_b128 v[194:197], v151 offset:50176
	ds_read_b128 v[198:201], v151 offset:51200
	ds_read_b128 v[202:205], v151 offset:52224
	ds_read_b128 v[206:209], v151 offset:53248
	ds_read_b128 v[210:213], v151 offset:54272
	ds_read_b128 v[214:217], v151 offset:55296
	ds_read_b128 v[218:221], v151 offset:56320
	s_add_u32 s98, s98, 128
	s_addc_u32 s99, s99, 0
	global_load_lds_dwordx4 v134, s[98:99]
	s_mov_b32 m0, s22
	s_nop 0
	global_load_lds_dwordx4 v136, s[98:99]
	s_barrier
	s_waitcnt lgkmcnt(0)
	s_waitcnt lgkmcnt(0)
	v_mfma_f32_16x16x32_bf16 v[62:65], v[170:173], v[190:193], v[62:65]
	v_mfma_f32_16x16x32_bf16 v[58:61], v[182:185], v[190:193], v[58:61]
	v_mfma_f32_16x16x32_bf16 v[46:49], v[170:173], v[198:201], v[46:49]
	v_mfma_f32_16x16x32_bf16 v[42:45], v[182:185], v[198:201], v[42:45]
	v_mfma_f32_16x16x32_bf16 v[30:33], v[170:173], v[206:209], v[30:33]
	v_mfma_f32_16x16x32_bf16 v[26:29], v[182:185], v[206:209], v[26:29]
	v_mfma_f32_16x16x32_bf16 v[14:17], v[170:173], v[214:217], v[14:17]
	v_mfma_f32_16x16x32_bf16 v[10:13], v[182:185], v[214:217], v[10:13]
	v_mfma_f32_16x16x32_bf16 v[62:65], v[174:177], v[194:197], v[62:65]
	v_mfma_f32_16x16x32_bf16 v[58:61], v[186:189], v[194:197], v[58:61]
	v_mfma_f32_16x16x32_bf16 v[46:49], v[174:177], v[202:205], v[46:49]
	v_mfma_f32_16x16x32_bf16 v[42:45], v[186:189], v[202:205], v[42:45]
	v_mfma_f32_16x16x32_bf16 v[30:33], v[174:177], v[210:213], v[30:33]
	v_mfma_f32_16x16x32_bf16 v[26:29], v[186:189], v[210:213], v[26:29]
	v_mfma_f32_16x16x32_bf16 v[14:17], v[174:177], v[218:221], v[14:17]
	v_mfma_f32_16x16x32_bf16 v[10:13], v[186:189], v[218:221], v[10:13]
	s_barrier
	s_add_u32 s2, s16, 0x40080
	s_addc_u32 s3, s17, 0
	s_add_i32 s16, s95, s5
	s_mov_b32 m0, s16
	s_nop 0
	global_load_lds_dwordx4 v154, s[2:3]
	s_add_i32 m0, s16, 0x2000
	s_nop 0
	global_load_lds_dwordx4 v138, s[2:3]
	s_waitcnt vmcnt(6)
	s_barrier
	v_mfma_f32_16x16x32_bf16 v[54:57], v[222:225], v[190:193], v[54:57]
	v_mfma_f32_16x16x32_bf16 v[50:53], v[230:233], v[190:193], v[50:53]
	v_mfma_f32_16x16x32_bf16 v[38:41], v[222:225], v[198:201], v[38:41]
	v_mfma_f32_16x16x32_bf16 v[34:37], v[230:233], v[198:201], v[34:37]
	v_mfma_f32_16x16x32_bf16 v[22:25], v[222:225], v[206:209], v[22:25]
	v_mfma_f32_16x16x32_bf16 v[18:21], v[230:233], v[206:209], v[18:21]
	v_mfma_f32_16x16x32_bf16 v[6:9], v[222:225], v[214:217], v[6:9]
	v_mfma_f32_16x16x32_bf16 v[2:5], v[230:233], v[214:217], v[2:5]
	v_mfma_f32_16x16x32_bf16 v[54:57], v[226:229], v[194:197], v[54:57]
	v_mfma_f32_16x16x32_bf16 v[50:53], v[234:237], v[194:197], v[50:53]
	v_mfma_f32_16x16x32_bf16 v[38:41], v[226:229], v[202:205], v[38:41]
	v_mfma_f32_16x16x32_bf16 v[34:37], v[234:237], v[202:205], v[34:37]
	v_mfma_f32_16x16x32_bf16 v[22:25], v[226:229], v[210:213], v[22:25]
	v_mfma_f32_16x16x32_bf16 v[18:21], v[234:237], v[210:213], v[18:21]
	v_mfma_f32_16x16x32_bf16 v[6:9], v[226:229], v[218:221], v[6:9]
	v_mfma_f32_16x16x32_bf16 v[2:5], v[234:237], v[218:221], v[2:5]
	s_add_i32 s39, s39, 2
	s_add_u32 s30, s30, 0x100
	s_addc_u32 s31, s31, 0
	s_add_u32 s28, s28, 0x100
	s_addc_u32 s29, s29, 0
	s_cmp_gt_u32 s39, 13
	s_barrier

.LHM_kdone:
	s_cmp_gt_i32 s10, 2
	s_cselect_b64 s[94:95], -1, 0
	s_mov_b64 s[28:29], -1
	s_and_b64 vcc, exec, s[94:95]
	s_cbranch_vccz .LBB0_638
	s_cmp_gt_u32 s10, 5
	s_mov_b64 s[30:31], -1
	s_cbranch_scc0 .LBB0_636
	s_cmp_gt_u32 s10, 8
	s_cbranch_scc0 .LBB0_633
	s_cmp_gt_u32 s10, 10
	s_mov_b64 s[2:3], -1
	s_cbranch_scc0 .LBB0_631
	s_cmp_lt_i32 s10, 12
	s_mov_b64 s[2:3], 0
	s_cbranch_scc1 .LBB0_630
	s_cmp_lg_u32 s10, 12
	s_mov_b64 s[16:17], -1
	s_cbranch_scc0 .LBB0_628
	s_mov_b64 s[16:17], 0

.LHM_kB:
	s_add_u32 s2, s30, 0xfffc0080
	s_addc_u32 s3, s31, -1
	s_add_i32 s94, 32, 0x10000
	v_add_u32_e32 v131, s94, v145
	ds_read_b128 v[170:173], v131
	ds_read_b128 v[174:177], v131 offset:1024
	ds_read_b128 v[182:185], v131 offset:2048
	ds_read_b128 v[186:189], v131 offset:3072
	s_cmp_eq_u32 s39, 12
	s_cselect_b32 s3, s11, s3
	s_cselect_b32 s2, s18, s2
	s_cselect_b32 s17, s13, s29
	s_cselect_b32 s16, s19, s28
	s_add_i32 m0, s35, 0xc000
	ds_read_b128 v[190:193], v151
	ds_read_b128 v[194:197], v151 offset:1024
	ds_read_b128 v[198:201], v151 offset:2048
	ds_read_b128 v[202:205], v151 offset:3072
	ds_read_b128 v[206:209], v151 offset:4096
	ds_read_b128 v[210:213], v151 offset:5120
	ds_read_b128 v[214:217], v151 offset:6144
	ds_read_b128 v[218:221], v151 offset:7168
	global_load_lds_dwordx4 v140, s[30:31]
	s_add_i32 m0, s35, 0xe000
	s_nop 0
	global_load_lds_dwordx4 v142, s[30:31]
	s_waitcnt lgkmcnt(8)
	s_barrier
	s_waitcnt lgkmcnt(0)
	s_waitcnt lgkmcnt(0)
	v_mfma_f32_16x16x32_bf16 v[126:129], v[170:173], v[190:193], 0
	v_mfma_f32_16x16x32_bf16 v[122:125], v[182:185], v[190:193], 0
	v_mfma_f32_16x16x32_bf16 v[110:113], v[170:173], v[198:201], 0
	v_mfma_f32_16x16x32_bf16 v[106:109], v[182:185], v[198:201], 0
	v_mfma_f32_16x16x32_bf16 v[94:97], v[170:173], v[206:209], 0
	v_mfma_f32_16x16x32_bf16 v[90:93], v[182:185], v[206:209], 0
	v_mfma_f32_16x16x32_bf16 v[78:81], v[170:173], v[214:217], 0
	v_mfma_f32_16x16x32_bf16 v[74:77], v[182:185], v[214:217], 0
	v_mfma_f32_16x16x32_bf16 v[126:129], v[174:177], v[194:197], v[126:129]
	v_mfma_f32_16x16x32_bf16 v[122:125], v[186:189], v[194:197], v[122:125]
	v_mfma_f32_16x16x32_bf16 v[110:113], v[174:177], v[202:205], v[110:113]
	v_mfma_f32_16x16x32_bf16 v[106:109], v[186:189], v[202:205], v[106:109]
	v_mfma_f32_16x16x32_bf16 v[94:97], v[174:177], v[210:213], v[94:97]
	v_mfma_f32_16x16x32_bf16 v[90:93], v[186:189], v[210:213], v[90:93]
	v_mfma_f32_16x16x32_bf16 v[78:81], v[174:177], v[218:221], v[78:81]
	v_mfma_f32_16x16x32_bf16 v[74:77], v[186:189], v[218:221], v[74:77]
	s_barrier
	s_add_i32 vcc_lo, 32, 0x14000
	s_add_i32 s94, s94, s5
	s_mov_b32 m0, s94
	global_load_lds_dwordx4 v154, s[16:17]
	s_add_i32 m0, s94, 0x2000
	s_nop 0
	global_load_lds_dwordx4 v138, s[16:17]
	s_barrier
	s_waitcnt lgkmcnt(0)
	s_waitcnt lgkmcnt(0)
	s_mov_b32 m0, s35
	s_mov_b64 s[98:99], s[2:3]
	s_barrier
	ds_read_b128 v[190:193], v151 offset:16384
	ds_read_b128 v[194:197], v151 offset:17408
	ds_read_b128 v[198:201], v151 offset:18432
	ds_read_b128 v[202:205], v151 offset:19456
	ds_read_b128 v[206:209], v151 offset:20480
	ds_read_b128 v[210:213], v151 offset:21504
	ds_read_b128 v[214:217], v151 offset:22528
	ds_read_b128 v[218:221], v151 offset:23552
	global_load_lds_dwordx4 v134, s[2:3]
	s_mov_b32 m0, s14
	s_nop 0
	global_load_lds_dwordx4 v136, s[2:3]
	s_barrier
	s_waitcnt lgkmcnt(0)
	s_waitcnt lgkmcnt(0)
	v_mfma_f32_16x16x32_bf16 v[62:65], v[170:173], v[190:193], 0
	v_mfma_f32_16x16x32_bf16 v[58:61], v[182:185], v[190:193], 0
	v_mfma_f32_16x16x32_bf16 v[46:49], v[170:173], v[198:201], 0
	v_mfma_f32_16x16x32_bf16 v[42:45], v[182:185], v[198:201], 0
	v_mfma_f32_16x16x32_bf16 v[30:33], v[170:173], v[206:209], 0
	v_mfma_f32_16x16x32_bf16 v[26:29], v[182:185], v[206:209], 0
	v_mfma_f32_16x16x32_bf16 v[14:17], v[170:173], v[214:217], 0
	v_mfma_f32_16x16x32_bf16 v[10:13], v[182:185], v[214:217], 0
	v_mfma_f32_16x16x32_bf16 v[62:65], v[174:177], v[194:197], v[62:65]
	v_mfma_f32_16x16x32_bf16 v[58:61], v[186:189], v[194:197], v[58:61]
	v_mfma_f32_16x16x32_bf16 v[46:49], v[174:177], v[202:205], v[46:49]
	v_mfma_f32_16x16x32_bf16 v[42:45], v[186:189], v[202:205], v[42:45]
	v_mfma_f32_16x16x32_bf16 v[30:33], v[174:177], v[210:213], v[30:33]
	v_mfma_f32_16x16x32_bf16 v[26:29], v[186:189], v[210:213], v[26:29]
	v_mfma_f32_16x16x32_bf16 v[14:17], v[174:177], v[218:221], v[14:17]
	v_mfma_f32_16x16x32_bf16 v[10:13], v[186:189], v[218:221], v[10:13]
	s_barrier
	s_add_u32 s94, s16, 0x40000
	s_addc_u32 s95, s17, 0
	s_add_i32 vcc_lo, vcc_lo, s5
	s_mov_b32 m0, vcc_lo
	s_nop 0
	s_add_i32 m0, vcc_lo, 0x2000
	s_nop 0
	s_waitcnt vmcnt(4)
	s_barrier
	s_add_i32 s94, 32, 0x18000
	s_barrier
	ds_read_b128 v[170:173], v131 offset:32768
	ds_read_b128 v[174:177], v131 offset:33792
	ds_read_b128 v[182:185], v131 offset:34816
	ds_read_b128 v[186:189], v131 offset:35840
	s_add_u32 s2, s2, 0x40000
	s_addc_u32 s3, s3, 0
	s_mov_b32 m0, s4
	ds_read_b128 v[190:193], v151 offset:32768
	ds_read_b128 v[194:197], v151 offset:33792
	ds_read_b128 v[198:201], v151 offset:34816
	ds_read_b128 v[202:205], v151 offset:35840
	ds_read_b128 v[206:209], v151 offset:36864
	ds_read_b128 v[210:213], v151 offset:37888
	ds_read_b128 v[214:217], v151 offset:38912
	ds_read_b128 v[218:221], v151 offset:39936
	global_load_lds_dwordx4 v134, s[2:3]
	s_mov_b32 m0, s20
	s_nop 0
	global_load_lds_dwordx4 v136, s[2:3]
	s_waitcnt lgkmcnt(8)
	s_barrier
	s_waitcnt lgkmcnt(0)
	s_waitcnt lgkmcnt(0)
	v_mfma_f32_16x16x32_bf16 v[126:129], v[170:173], v[190:193], v[126:129]
	v_mfma_f32_16x16x32_bf16 v[122:125], v[182:185], v[190:193], v[122:125]
	v_mfma_f32_16x16x32_bf16 v[110:113], v[170:173], v[198:201], v[110:113]
	v_mfma_f32_16x16x32_bf16 v[106:109], v[182:185], v[198:201], v[106:109]
	v_mfma_f32_16x16x32_bf16 v[94:97], v[170:173], v[206:209], v[94:97]
	v_mfma_f32_16x16x32_bf16 v[90:93], v[182:185], v[206:209], v[90:93]
	v_mfma_f32_16x16x32_bf16 v[78:81], v[170:173], v[214:217], v[78:81]
	v_mfma_f32_16x16x32_bf16 v[74:77], v[182:185], v[214:217], v[74:77]
	v_mfma_f32_16x16x32_bf16 v[126:129], v[174:177], v[194:197], v[126:129]
	v_mfma_f32_16x16x32_bf16 v[122:125], v[186:189], v[194:197], v[122:125]
	v_mfma_f32_16x16x32_bf16 v[110:113], v[174:177], v[202:205], v[110:113]
	v_mfma_f32_16x16x32_bf16 v[106:109], v[186:189], v[202:205], v[106:109]
	v_mfma_f32_16x16x32_bf16 v[94:97], v[174:177], v[210:213], v[94:97]
	v_mfma_f32_16x16x32_bf16 v[90:93], v[186:189], v[210:213], v[90:93]
	v_mfma_f32_16x16x32_bf16 v[78:81], v[174:177], v[218:221], v[78:81]
	v_mfma_f32_16x16x32_bf16 v[74:77], v[186:189], v[218:221], v[74:77]
	s_barrier
	s_add_i32 s95, 32, 0x1c000
	s_add_i32 s2, s94, s5
	s_mov_b32 m0, s2
	s_add_u32 s100, s16, 128
	s_addc_u32 s101, s17, 0
	global_load_lds_dwordx4 v154, s[100:101]
	s_add_i32 m0, s2, 0x2000
	s_nop 0
	global_load_lds_dwordx4 v138, s[100:101]
	s_barrier
	s_waitcnt lgkmcnt(0)
	s_waitcnt lgkmcnt(0)
	s_mov_b32 m0, s21
	s_barrier
	ds_read_b128 v[190:193], v151 offset:49152
	ds_read_b128 v[194:197], v151 offset:50176
	ds_read_b128 v[198:201], v151 offset:51200
	ds_read_b128 v[202:205], v151 offset:52224
	ds_read_b128 v[206:209], v151 offset:53248
	ds_read_b128 v[210:213], v151 offset:54272
	ds_read_b128 v[214:217], v151 offset:55296
	ds_read_b128 v[218:221], v151 offset:56320
	s_add_u32 s98, s98, 128
	s_addc_u32 s99, s99, 0
	global_load_lds_dwordx4 v134, s[98:99]
	s_mov_b32 m0, s22
	s_nop 0
	global_load_lds_dwordx4 v136, s[98:99]
	s_barrier
	s_waitcnt lgkmcnt(0)
	s_waitcnt lgkmcnt(0)
	v_mfma_f32_16x16x32_bf16 v[62:65], v[170:173], v[190:193], v[62:65]
	v_mfma_f32_16x16x32_bf16 v[58:61], v[182:185], v[190:193], v[58:61]
	v_mfma_f32_16x16x32_bf16 v[46:49], v[170:173], v[198:201], v[46:49]
	v_mfma_f32_16x16x32_bf16 v[42:45], v[182:185], v[198:201], v[42:45]
	v_mfma_f32_16x16x32_bf16 v[30:33], v[170:173], v[206:209], v[30:33]
	v_mfma_f32_16x16x32_bf16 v[26:29], v[182:185], v[206:209], v[26:29]
	v_mfma_f32_16x16x32_bf16 v[14:17], v[170:173], v[214:217], v[14:17]
	v_mfma_f32_16x16x32_bf16 v[10:13], v[182:185], v[214:217], v[10:13]
	v_mfma_f32_16x16x32_bf16 v[62:65], v[174:177], v[194:197], v[62:65]
	v_mfma_f32_16x16x32_bf16 v[58:61], v[186:189], v[194:197], v[58:61]
	v_mfma_f32_16x16x32_bf16 v[46:49], v[174:177], v[202:205], v[46:49]
	v_mfma_f32_16x16x32_bf16 v[42:45], v[186:189], v[202:205], v[42:45]
	v_mfma_f32_16x16x32_bf16 v[30:33], v[174:177], v[210:213], v[30:33]
	v_mfma_f32_16x16x32_bf16 v[26:29], v[186:189], v[210:213], v[26:29]
	v_mfma_f32_16x16x32_bf16 v[14:17], v[174:177], v[218:221], v[14:17]
	v_mfma_f32_16x16x32_bf16 v[10:13], v[186:189], v[218:221], v[10:13]
	s_barrier
	s_add_u32 s2, s16, 0x40080
	s_addc_u32 s3, s17, 0
	s_add_i32 s16, s95, s5
	s_mov_b32 m0, s16
	s_nop 0
	s_add_i32 m0, s16, 0x2000
	s_nop 0
	s_waitcnt vmcnt(4)
	s_barrier
	s_add_i32 s39, s39, 2
	s_add_u32 s30, s30, 0x100
	s_addc_u32 s31, s31, 0
	s_add_u32 s28, s28, 0x100
	s_addc_u32 s29, s29, 0
	s_cmp_gt_u32 s39, 13
	s_barrier
.LHM_lpB:
	s_add_u32 s2, s30, 0xfffc0080
	s_addc_u32 s3, s31, -1
	s_add_i32 s94, 32, 0x10000
	v_add_u32_e32 v131, s94, v145
	ds_read_b128 v[170:173], v131
	ds_read_b128 v[174:177], v131 offset:1024
	ds_read_b128 v[182:185], v131 offset:2048
	ds_read_b128 v[186:189], v131 offset:3072
	s_cmp_eq_u32 s39, 12
	s_cselect_b32 s3, s11, s3
	s_cselect_b32 s2, s18, s2
	s_cselect_b32 s17, s13, s29
	s_cselect_b32 s16, s19, s28
	s_add_i32 m0, s35, 0xc000
	ds_read_b128 v[190:193], v151
	ds_read_b128 v[194:197], v151 offset:1024
	ds_read_b128 v[198:201], v151 offset:2048
	ds_read_b128 v[202:205], v151 offset:3072
	ds_read_b128 v[206:209], v151 offset:4096
	ds_read_b128 v[210:213], v151 offset:5120
	ds_read_b128 v[214:217], v151 offset:6144
	ds_read_b128 v[218:221], v151 offset:7168
	global_load_lds_dwordx4 v140, s[30:31]
	s_add_i32 m0, s35, 0xe000
	s_nop 0
	global_load_lds_dwordx4 v142, s[30:31]
	s_waitcnt lgkmcnt(8)
	s_barrier
	s_waitcnt lgkmcnt(0)
	s_waitcnt lgkmcnt(0)
	v_mfma_f32_16x16x32_bf16 v[126:129], v[170:173], v[190:193], v[126:129]
	v_mfma_f32_16x16x32_bf16 v[122:125], v[182:185], v[190:193], v[122:125]
	v_mfma_f32_16x16x32_bf16 v[110:113], v[170:173], v[198:201], v[110:113]
	v_mfma_f32_16x16x32_bf16 v[106:109], v[182:185], v[198:201], v[106:109]
	v_mfma_f32_16x16x32_bf16 v[94:97], v[170:173], v[206:209], v[94:97]
	v_mfma_f32_16x16x32_bf16 v[90:93], v[182:185], v[206:209], v[90:93]
	v_mfma_f32_16x16x32_bf16 v[78:81], v[170:173], v[214:217], v[78:81]
	v_mfma_f32_16x16x32_bf16 v[74:77], v[182:185], v[214:217], v[74:77]
	v_mfma_f32_16x16x32_bf16 v[126:129], v[174:177], v[194:197], v[126:129]
	v_mfma_f32_16x16x32_bf16 v[122:125], v[186:189], v[194:197], v[122:125]
	v_mfma_f32_16x16x32_bf16 v[110:113], v[174:177], v[202:205], v[110:113]
	v_mfma_f32_16x16x32_bf16 v[106:109], v[186:189], v[202:205], v[106:109]
	v_mfma_f32_16x16x32_bf16 v[94:97], v[174:177], v[210:213], v[94:97]
	v_mfma_f32_16x16x32_bf16 v[90:93], v[186:189], v[210:213], v[90:93]
	v_mfma_f32_16x16x32_bf16 v[78:81], v[174:177], v[218:221], v[78:81]
	v_mfma_f32_16x16x32_bf16 v[74:77], v[186:189], v[218:221], v[74:77]
	s_barrier
	s_add_i32 vcc_lo, 32, 0x14000
	s_add_i32 s94, s94, s5
	s_mov_b32 m0, s94
	global_load_lds_dwordx4 v154, s[16:17]
	s_add_i32 m0, s94, 0x2000
	s_nop 0
	global_load_lds_dwordx4 v138, s[16:17]
	s_barrier
	s_waitcnt lgkmcnt(0)
	s_waitcnt lgkmcnt(0)
	s_mov_b32 m0, s35
	s_mov_b64 s[98:99], s[2:3]
	s_barrier
	ds_read_b128 v[190:193], v151 offset:16384
	ds_read_b128 v[194:197], v151 offset:17408
	ds_read_b128 v[198:201], v151 offset:18432
	ds_read_b128 v[202:205], v151 offset:19456
	ds_read_b128 v[206:209], v151 offset:20480
	ds_read_b128 v[210:213], v151 offset:21504
	ds_read_b128 v[214:217], v151 offset:22528
	ds_read_b128 v[218:221], v151 offset:23552
	global_load_lds_dwordx4 v134, s[2:3]
	s_mov_b32 m0, s14
	s_nop 0
	global_load_lds_dwordx4 v136, s[2:3]
	s_barrier
	s_waitcnt lgkmcnt(0)
	s_waitcnt lgkmcnt(0)
	v_mfma_f32_16x16x32_bf16 v[62:65], v[170:173], v[190:193], v[62:65]
	v_mfma_f32_16x16x32_bf16 v[58:61], v[182:185], v[190:193], v[58:61]
	v_mfma_f32_16x16x32_bf16 v[46:49], v[170:173], v[198:201], v[46:49]
	v_mfma_f32_16x16x32_bf16 v[42:45], v[182:185], v[198:201], v[42:45]
	v_mfma_f32_16x16x32_bf16 v[30:33], v[170:173], v[206:209], v[30:33]
	v_mfma_f32_16x16x32_bf16 v[26:29], v[182:185], v[206:209], v[26:29]
	v_mfma_f32_16x16x32_bf16 v[14:17], v[170:173], v[214:217], v[14:17]
	v_mfma_f32_16x16x32_bf16 v[10:13], v[182:185], v[214:217], v[10:13]
	v_mfma_f32_16x16x32_bf16 v[62:65], v[174:177], v[194:197], v[62:65]
	v_mfma_f32_16x16x32_bf16 v[58:61], v[186:189], v[194:197], v[58:61]
	v_mfma_f32_16x16x32_bf16 v[46:49], v[174:177], v[202:205], v[46:49]
	v_mfma_f32_16x16x32_bf16 v[42:45], v[186:189], v[202:205], v[42:45]
	v_mfma_f32_16x16x32_bf16 v[30:33], v[174:177], v[210:213], v[30:33]
	v_mfma_f32_16x16x32_bf16 v[26:29], v[186:189], v[210:213], v[26:29]
	v_mfma_f32_16x16x32_bf16 v[14:17], v[174:177], v[218:221], v[14:17]
	v_mfma_f32_16x16x32_bf16 v[10:13], v[186:189], v[218:221], v[10:13]
	s_barrier
	s_add_u32 s94, s16, 0x40000
	s_addc_u32 s95, s17, 0
	s_add_i32 vcc_lo, vcc_lo, s5
	s_mov_b32 m0, vcc_lo
	s_nop 0
	s_cmp_eq_u32 s39, 12
	s_cbranch_scc0 .LHM_nb23
	global_load_lds_dwordx4 v154, s[94:95]
	s_add_i32 m0, vcc_lo, 0x2000
	s_nop 0
	global_load_lds_dwordx4 v138, s[94:95]
.LHM_nb23:
	s_waitcnt vmcnt(4)
	s_barrier
	s_add_i32 s94, 32, 0x18000
	s_barrier
	ds_read_b128 v[170:173], v131 offset:32768
	ds_read_b128 v[174:177], v131 offset:33792
	ds_read_b128 v[182:185], v131 offset:34816
	ds_read_b128 v[186:189], v131 offset:35840
	s_add_u32 s2, s2, 0x40000
	s_addc_u32 s3, s3, 0
	s_mov_b32 m0, s4
	ds_read_b128 v[190:193], v151 offset:32768
	ds_read_b128 v[194:197], v151 offset:33792
	ds_read_b128 v[198:201], v151 offset:34816
	ds_read_b128 v[202:205], v151 offset:35840
	ds_read_b128 v[206:209], v151 offset:36864
	ds_read_b128 v[210:213], v151 offset:37888
	ds_read_b128 v[214:217], v151 offset:38912
	ds_read_b128 v[218:221], v151 offset:39936
	global_load_lds_dwordx4 v134, s[2:3]
	s_mov_b32 m0, s20
	s_nop 0
	global_load_lds_dwordx4 v136, s[2:3]
	s_waitcnt lgkmcnt(8)
	s_barrier
	s_waitcnt lgkmcnt(0)
	s_waitcnt lgkmcnt(0)
	v_mfma_f32_16x16x32_bf16 v[126:129], v[170:173], v[190:193], v[126:129]
	v_mfma_f32_16x16x32_bf16 v[122:125], v[182:185], v[190:193], v[122:125]
	v_mfma_f32_16x16x32_bf16 v[110:113], v[170:173], v[198:201], v[110:113]
	v_mfma_f32_16x16x32_bf16 v[106:109], v[182:185], v[198:201], v[106:109]
	v_mfma_f32_16x16x32_bf16 v[94:97], v[170:173], v[206:209], v[94:97]
	v_mfma_f32_16x16x32_bf16 v[90:93], v[182:185], v[206:209], v[90:93]
	v_mfma_f32_16x16x32_bf16 v[78:81], v[170:173], v[214:217], v[78:81]
	v_mfma_f32_16x16x32_bf16 v[74:77], v[182:185], v[214:217], v[74:77]
	v_mfma_f32_16x16x32_bf16 v[126:129], v[174:177], v[194:197], v[126:129]
	v_mfma_f32_16x16x32_bf16 v[122:125], v[186:189], v[194:197], v[122:125]
	v_mfma_f32_16x16x32_bf16 v[110:113], v[174:177], v[202:205], v[110:113]
	v_mfma_f32_16x16x32_bf16 v[106:109], v[186:189], v[202:205], v[106:109]
	v_mfma_f32_16x16x32_bf16 v[94:97], v[174:177], v[210:213], v[94:97]
	v_mfma_f32_16x16x32_bf16 v[90:93], v[186:189], v[210:213], v[90:93]
	v_mfma_f32_16x16x32_bf16 v[78:81], v[174:177], v[218:221], v[78:81]
	v_mfma_f32_16x16x32_bf16 v[74:77], v[186:189], v[218:221], v[74:77]
	s_barrier
	s_add_i32 s95, 32, 0x1c000
	s_add_i32 s2, s94, s5
	s_mov_b32 m0, s2
	s_add_u32 s100, s16, 128
	s_addc_u32 s101, s17, 0
	global_load_lds_dwordx4 v154, s[100:101]
	s_add_i32 m0, s2, 0x2000
	s_nop 0
	global_load_lds_dwordx4 v138, s[100:101]
	s_barrier
	s_waitcnt lgkmcnt(0)
	s_waitcnt lgkmcnt(0)
	s_mov_b32 m0, s21
	s_barrier
	ds_read_b128 v[190:193], v151 offset:49152
	ds_read_b128 v[194:197], v151 offset:50176
	ds_read_b128 v[198:201], v151 offset:51200
	ds_read_b128 v[202:205], v151 offset:52224
	ds_read_b128 v[206:209], v151 offset:53248
	ds_read_b128 v[210:213], v151 offset:54272
	ds_read_b128 v[214:217], v151 offset:55296
	ds_read_b128 v[218:221], v151 offset:56320
	s_add_u32 s98, s98, 128
	s_addc_u32 s99, s99, 0
	global_load_lds_dwordx4 v134, s[98:99]
	s_mov_b32 m0, s22
	s_nop 0
	global_load_lds_dwordx4 v136, s[98:99]
	s_barrier
	s_waitcnt lgkmcnt(0)
	s_waitcnt lgkmcnt(0)
	v_mfma_f32_16x16x32_bf16 v[62:65], v[170:173], v[190:193], v[62:65]
	v_mfma_f32_16x16x32_bf16 v[58:61], v[182:185], v[190:193], v[58:61]
	v_mfma_f32_16x16x32_bf16 v[46:49], v[170:173], v[198:201], v[46:49]
	v_mfma_f32_16x16x32_bf16 v[42:45], v[182:185], v[198:201], v[42:45]
	v_mfma_f32_16x16x32_bf16 v[30:33], v[170:173], v[206:209], v[30:33]
	v_mfma_f32_16x16x32_bf16 v[26:29], v[182:185], v[206:209], v[26:29]
	v_mfma_f32_16x16x32_bf16 v[14:17], v[170:173], v[214:217], v[14:17]
	v_mfma_f32_16x16x32_bf16 v[10:13], v[182:185], v[214:217], v[10:13]
	v_mfma_f32_16x16x32_bf16 v[62:65], v[174:177], v[194:197], v[62:65]
	v_mfma_f32_16x16x32_bf16 v[58:61], v[186:189], v[194:197], v[58:61]
	v_mfma_f32_16x16x32_bf16 v[46:49], v[174:177], v[202:205], v[46:49]
	v_mfma_f32_16x16x32_bf16 v[42:45], v[186:189], v[202:205], v[42:45]
	v_mfma_f32_16x16x32_bf16 v[30:33], v[174:177], v[210:213], v[30:33]
	v_mfma_f32_16x16x32_bf16 v[26:29], v[186:189], v[210:213], v[26:29]
	v_mfma_f32_16x16x32_bf16 v[14:17], v[174:177], v[218:221], v[14:17]
	v_mfma_f32_16x16x32_bf16 v[10:13], v[186:189], v[218:221], v[10:13]
	s_barrier
	s_add_u32 s2, s16, 0x40080
	s_addc_u32 s3, s17, 0
	s_add_i32 s16, s95, s5
	s_mov_b32 m0, s16
	s_nop 0
	s_cmp_eq_u32 s39, 12
	s_cbranch_scc0 .LHM_nb31
	global_load_lds_dwordx4 v154, s[2:3]
	s_add_i32 m0, s16, 0x2000
	s_nop 0
	global_load_lds_dwordx4 v138, s[2:3]
.LHM_nb31:
	s_waitcnt vmcnt(4)
	s_barrier
	s_add_i32 s39, s39, 2
	s_add_u32 s30, s30, 0x100
	s_addc_u32 s31, s31, 0
	s_add_u32 s28, s28, 0x100
	s_addc_u32 s29, s29, 0
	s_cmp_gt_u32 s39, 13
	s_barrier
	s_cbranch_scc0 .LHM_lpB
	s_branch .LHM_kdone
